# stage 3 tail rebalanced: skinny_glu / skinny_pool tasks moved to pool-mixer workgroups (which now have slack after the pool epilogue pool_scale hoist)
# baseline (speedup 1.0000x reference)
; __device__ __forceinline__ unsigned xb_ld(unsigned* p)              { return __hip_atomic_load(p, __ATOMIC_RELAXED, __HIP_MEMORY_SCOPE_AGENT); }
; __device__ __forceinline__ void xcd_barrier_complete(unsigned* bar, unsigned x, unsigned& nloc, unsigned& nx) {
;     ...
; #pragma unroll
;         for (unsigned j = 0; j < 16; ++j) { const unsigned c = xb_ld(&bar[XB_XCNT(j)]); sum += c; cnt += (c > 0u) ? 1u : 0u; mine = (j == x) ? c : mine; }
;     __device__ bool next(int i, Unit& u) const {
;         long L; int z;
;         if (zin) { z = i % nz; L = (long)(i / nz) * G + c; if (L >= ntile) return false; }
;         else { const long LL = (long)i * G + c; if (LL >= (long)ntile * nz) return false; z = (int)(LL / ntile); L = LL % ntile; }
;         int wgid = (int)L; { const int q = ntile / NXCD, r = ntile % NXCD, xcd = wgid % NXCD, off = wgid / NXCD; wgid = (xcd < r ? xcd * (q + 1) : r * (q + 1) + (xcd - r) * q) + off; }
;         const int nig = WGM * nN, gid = wgid / nig, fm = gid * WGM, gsz = (nM - fm) < WGM ? (nM - fm) : WGM;
;         u.pm = fm + ((wgid % nig) % gsz); u.pn = (wgid % nig) / gsz; u.z = z; return true;
.LBB0_140:
	s_cmpk_lt_i32 s92, 0x6e0
	s_cselect_b64 s[4:5], -1, 0
	v_writelane_b32 v252, s4, 14
	s_mul_hi_i32 s3, s92, 0x94f2095
	s_ashr_i32 s85, s84, 31
	v_writelane_b32 v252, s5, 15
	s_lshr_b32 s4, s3, 31
	s_lshr_b32 s3, s3, 6
	s_add_i32 s3, s3, s4
	s_mulk_i32 s3, 0x6e0
	s_sub_i32 s3, s92, s3
	s_sext_i32_i16 s4, s3
	s_bfe_u32 s4, s4, 0x3001c
	s_add_i32 s4, s3, s4
	s_and_b32 s5, s4, 0xfff8
	s_sub_i32 s5, s3, s5
	s_sext_i32_i16 s3, s4
	v_readlane_b32 s8, v252, 0
	s_ashr_i32 s4, s3, 3
	s_ashr_i32 s93, s92, 31
	s_not_b32 s3, s92
	v_readlane_b32 s10, v252, 2
	v_readlane_b32 s11, v252, 3
	s_add_u32 s6, s10, 0x4200
	s_addc_u32 s7, s11, 0
	v_readlane_b32 s9, v252, 1
	v_writelane_b32 v252, s6, 16
	s_sext_i32_i16 s5, s5
	v_mov_b32_e32 v99, 0
	v_writelane_b32 v252, s7, 17
	s_add_u32 s6, s10, 0x4400
	s_addc_u32 s7, s11, 0
	v_writelane_b32 v252, s6, 18
	v_mov_b32_e32 v232, 1
	v_mov_b32_e32 v197, 2.0
	v_writelane_b32 v252, s7, 19
	s_add_u32 s6, s10, 0x4500
	s_addc_u32 s7, s11, 0
	v_writelane_b32 v252, s6, 20
	v_mov_b32_e32 v233, 0xff800000
	v_mov_b32_e32 v234, 0x358637bd
	v_writelane_b32 v252, s7, 21
	s_add_u32 s6, s10, 0x4600
	s_addc_u32 s7, s11, 0
	v_writelane_b32 v252, s6, 22
	v_mov_b32_e32 v235, 0x260
	v_mov_b32_e32 v237, 0x37000
	v_writelane_b32 v252, s7, 23
	s_add_u32 s6, s10, 0x4700
	s_addc_u32 s7, s11, 0
	v_writelane_b32 v252, s6, 24
	v_mov_b32_e32 v238, 0x80400
	v_mov_b32_e32 v239, 0x6e00
	v_writelane_b32 v252, s7, 25
	s_add_u32 s6, s10, 0x4800
	s_addc_u32 s7, s11, 0
	v_writelane_b32 v252, s6, 26
	v_mov_b32_e32 v240, 0xf000
	v_mov_b32_e32 v241, 0x80000001
	v_writelane_b32 v252, s7, 27
	s_add_u32 s6, s10, 0x4900
	s_addc_u32 s7, s11, 0
	v_writelane_b32 v252, s6, 28
	v_mov_b64_e32 v[204:205], 0xff
	s_movk_i32 s86, 0x80
	v_writelane_b32 v252, s7, 29
	s_add_u32 s6, s10, 0x4a00
	s_addc_u32 s7, s11, 0
	v_writelane_b32 v252, s6, 30
	s_movk_i32 s87, 0x6e00
	s_movk_i32 s56, 0xc00
	v_writelane_b32 v252, s7, 31
	s_add_u32 s6, s10, 0x4b00
	s_addc_u32 s7, s11, 0
	v_writelane_b32 v252, s6, 32
	s_mov_b32 s57, 0xc802000
	s_mov_b32 s38, 0x40000
	v_writelane_b32 v252, s7, 33
	s_add_u32 s6, s10, 0x4c00
	s_addc_u32 s7, s11, 0
	v_writelane_b32 v252, s6, 34
	s_mov_b32 s90, 0x2b900000
	s_mov_b32 s33, 0x41000000
	v_writelane_b32 v252, s7, 35
	s_add_u32 s6, s10, 0x4d00
	s_addc_u32 s7, s11, 0
	v_writelane_b32 v252, s6, 36
	s_movk_i32 s78, 0x183
	s_movk_i32 s79, 0x37f
	v_writelane_b32 v252, s7, 37
	s_add_u32 s6, s10, 0x4e00
	s_addc_u32 s7, s11, 0
	v_writelane_b32 v252, s6, 38
	s_movk_i32 s80, 0x810
	s_mov_b64 s[62:63], 0x80
	v_writelane_b32 v252, s7, 39
	s_add_u32 s6, s10, 0x4f00
	s_addc_u32 s7, s11, 0
	v_writelane_b32 v252, s6, 40
	s_mov_b64 s[94:95], 0x2000
	s_mov_b64 s[96:97], 0x1000
	v_writelane_b32 v252, s7, 41
	s_add_u32 s6, s10, 0x5000
	s_addc_u32 s7, s11, 0
	v_writelane_b32 v252, s6, 42
	s_nop 1
	v_writelane_b32 v252, s7, 43
	s_add_u32 s6, s10, 0x5100
	s_addc_u32 s7, s11, 0
	v_writelane_b32 v252, s6, 44
	s_nop 1
	v_writelane_b32 v252, s7, 45
	s_add_u32 s6, s10, 0x5200
	s_addc_u32 s7, s11, 0
	v_writelane_b32 v252, s6, 46
	s_nop 1
	v_writelane_b32 v252, s7, 47
	s_add_u32 s6, s10, 0x5300
	s_addc_u32 s7, s11, 0
	v_writelane_b32 v252, s6, 48
	s_cmp_eq_u32 s2, 15
	s_nop 0
	v_writelane_b32 v252, s7, 49
	s_cselect_b64 s[6:7], -1, 0
	v_writelane_b32 v252, s6, 50
	s_cmp_eq_u32 s2, 14
	s_nop 0
	v_writelane_b32 v252, s7, 51
	s_cselect_b64 s[6:7], -1, 0
	v_writelane_b32 v252, s6, 52
	s_cmp_eq_u32 s2, 13
	s_nop 0
	v_writelane_b32 v252, s7, 53
	s_cselect_b64 s[6:7], -1, 0
	v_writelane_b32 v252, s6, 54
	s_cmp_eq_u32 s2, 12
	s_nop 0
	v_writelane_b32 v252, s7, 55
	s_cselect_b64 s[6:7], -1, 0
	v_writelane_b32 v252, s6, 56
	s_cmp_eq_u32 s2, 11
	s_nop 0
	v_writelane_b32 v252, s7, 57
	s_cselect_b64 s[6:7], -1, 0
	v_writelane_b32 v252, s6, 58
	s_cmp_eq_u32 s2, 10
	s_nop 0
	v_writelane_b32 v252, s7, 59
	s_cselect_b64 s[6:7], -1, 0
	v_writelane_b32 v252, s6, 60
	s_cmp_eq_u32 s2, 9
	s_nop 0
	v_writelane_b32 v252, s7, 61
	s_cselect_b64 s[6:7], -1, 0
	v_writelane_b32 v252, s6, 62
	s_cmp_eq_u32 s2, 8
	s_nop 0
	v_writelane_b32 v252, s7, 63
	s_cselect_b64 s[6:7], -1, 0
	v_writelane_b32 v253, s6, 0
	s_cmp_eq_u32 s2, 7
	s_nop 0
	v_writelane_b32 v253, s7, 1
	s_cselect_b64 s[6:7], -1, 0
	v_writelane_b32 v253, s6, 2
	s_cmp_eq_u32 s2, 6
	s_nop 0
	v_writelane_b32 v253, s7, 3
	s_cselect_b64 s[6:7], -1, 0
	v_writelane_b32 v253, s6, 4
	s_cmp_eq_u32 s2, 5
	s_nop 0
	v_writelane_b32 v253, s7, 5
	s_cselect_b64 s[6:7], -1, 0
	v_writelane_b32 v253, s6, 6
	s_cmp_eq_u32 s2, 4
	s_nop 0
	v_writelane_b32 v253, s7, 7
	s_cselect_b64 s[6:7], -1, 0
	v_writelane_b32 v253, s6, 8
	s_cmp_eq_u32 s2, 3
	s_nop 0
	v_writelane_b32 v253, s7, 9
	s_cselect_b64 s[6:7], -1, 0
	v_writelane_b32 v253, s6, 10
	s_cmp_eq_u32 s2, 2
	s_nop 0
	v_writelane_b32 v253, s7, 11
	s_cselect_b64 s[6:7], -1, 0
	v_writelane_b32 v253, s6, 12
	s_cmp_eq_u32 s2, 1
	s_nop 0
	v_writelane_b32 v253, s7, 13
	s_cselect_b64 s[6:7], -1, 0
	v_writelane_b32 v253, s6, 14
	s_cmp_eq_u32 s2, 0
	s_nop 0
	v_writelane_b32 v253, s7, 15
	s_cselect_b64 s[6:7], -1, 0
	s_lshl_b32 s2, s2, 8
	v_writelane_b32 v253, s6, 16
	s_add_u32 s2, s48, s2
	s_nop 0
	v_writelane_b32 v253, s7, 17
	s_addc_u32 s6, s49, 0
	s_add_u32 s8, s2, 0x1400
	s_addc_u32 s9, s6, 0
	v_writelane_b32 v253, s8, 18
	s_nop 1
	v_writelane_b32 v253, s9, 19
	s_add_u32 s8, s2, 0x2400
	s_addc_u32 s9, s6, 0
	v_writelane_b32 v253, s8, 20
	s_add_u32 s6, s10, 0x7400
	s_addc_u32 s7, s11, 0
	v_writelane_b32 v253, s9, 21
	v_writelane_b32 v253, s6, 22
	s_nop 1
	v_writelane_b32 v253, s7, 23
	s_add_u32 s6, s10, 0x7500
	s_addc_u32 s7, s11, 0
	v_writelane_b32 v253, s6, 24
	s_bfe_u32 s2, s92, 0x10003
	s_nop 0
	v_writelane_b32 v253, s7, 25
; __device__ __forceinline__ void skinny_glu(Frame& F, int l) {
;     ...
;     for (int task = F.G - 17 - F.bid; task < 8; task += F.G) {
;         if (task < 0) continue;
; __global__ void __launch_bounds__(NT, 2) fwd_kernel(Args args) {
;     ...
;             const int hi = (F.bid >> 3) & 1, idx = (F.bid >> 4) * 8 + (F.bid & 7);
;             const int n1 = (F.G >> 4) * 8 + ((F.G & 15) > 8 ? (F.G & 15) - 8 : 0), n0 = F.G - n1;
	v_writelane_b32 v253, s2, 26
	s_lshl_b32 s2, s92, 9
	s_cmpk_lt_i32 s92, 0x100
	v_writelane_b32 v253, s2, 27
	s_cselect_b64 s[6:7], -1, 0
	v_writelane_b32 v253, s6, 28
	s_ashr_i32 s2, s92, 1
	s_and_b32 s2, s2, -8
	v_writelane_b32 v253, s7, 29
	s_and_b32 s6, s92, 7
	s_or_b32 s13, s2, s6
	s_and_b32 s2, s84, 15
	v_sub_u32_e64 v1, s2, 8 clamp
	s_ashr_i32 s2, s84, 1
	s_and_b32 s2, s2, -8
	v_readfirstlane_b32 s6, v1
	s_or_b32 s2, s2, s6
	s_sub_i32 s14, s84, s2
	s_and_b32 s6, s92, 8
	s_cmp_eq_u32 s6, 0
	s_cselect_b64 s[8:9], -1, 0
	s_cmp_lg_u32 s6, 0
	v_writelane_b32 v253, s8, 30
	s_cselect_b64 s[6:7], -1, 0
	s_cmp_eq_u32 s2, 0
	v_writelane_b32 v253, s9, 31
	s_cselect_b64 s[8:9], -1, 0
	s_and_b64 s[10:11], s[8:9], exec
	s_cselect_b32 s10, s84, s2
	s_cselect_b32 s11, s92, s13
	s_or_b64 s[6:7], s[6:7], s[8:9]
	v_writelane_b32 v253, s6, 32
	s_cmpk_lt_i32 s11, 0x80
	s_nop 0
	v_writelane_b32 v253, s7, 33
	s_cselect_b64 s[6:7], -1, 0
	v_writelane_b32 v253, s6, 34
	s_ashr_i32 s2, s11, 31
	s_ashr_i32 s9, s10, 31
	v_writelane_b32 v253, s7, 35
	v_writelane_b32 v253, s2, 36
	s_lshr_b32 s2, s2, 25
	s_add_i32 s2, s11, s2
	s_and_b32 s2, s2, 0xff80
	s_sub_i32 s2, s11, s2
	s_bfe_i32 s6, s2, 0x80000
	s_bfe_u32 s6, s6, 0x3000c
	s_add_i32 s6, s2, s6
	s_and_b32 s7, s6, 0xfff8
	s_sub_i32 s2, s2, s7
	s_bfe_i32 s6, s6, 0x80000
	s_sext_i32_i8 s7, s2
	s_sext_i32_i16 s6, s6
	v_writelane_b32 v253, s11, 37
	s_bfe_i32 s2, s2, 0x80000
	s_ashr_i32 s6, s6, 3
	s_lshl_b32 s8, s7, 4
	v_writelane_b32 v253, s10, 38
	s_cmpk_lt_i32 s13, 0x80
	v_writelane_b32 v253, s9, 39
	s_cselect_b64 s[10:11], -1, 0
	v_writelane_b32 v253, s10, 40
	s_lshr_b32 s9, s93, 27
	s_add_i32 s9, s13, s9
	v_writelane_b32 v253, s11, 41
	s_and_b32 s10, s9, 0xffe0
	v_writelane_b32 v253, s14, 42
	s_ashr_i32 s14, s14, 31
	s_sub_i32 s10, s13, s10
	s_ashr_i32 s16, s9, 5
	v_writelane_b32 v253, s14, 43
	s_bfe_i32 s11, s10, 0x80000
	s_ashr_i32 s17, s16, 31
	v_writelane_b32 v253, s13, 44
	s_ashr_i32 s13, s13, 31
	s_bfe_u32 s11, s11, 0x3000c
	v_writelane_b32 v253, s13, 45
	s_lshl_b64 s[18:19], s[16:17], 9
	s_add_i32 s11, s10, s11
	s_sub_i32 s9, s84, s92
	v_writelane_b32 v253, s18, 46
	s_and_b32 s12, s11, 0xfff8
	s_sub_i32 s15, s9, 9
	v_writelane_b32 v253, s19, 47
	s_mov_b32 s14, s16
	s_sub_i32 s10, s10, s12
	s_bfe_i32 s11, s11, 0x80000
	v_writelane_b32 v253, s14, 48
	s_sext_i32_i8 s12, s10
	s_sext_i32_i16 s11, s11
	v_writelane_b32 v253, s15, 49
	s_lshl_b64 s[16:17], s[16:17], 17
	s_bfe_i32 s10, s10, 0x80000
	s_ashr_i32 s11, s11, 3
	s_lshl_b32 s9, s12, 2
	v_writelane_b32 v253, s16, 50
	s_cmp_lt_i32 s15, 8
	s_sext_i32_i16 s2, s2
	v_writelane_b32 v253, s17, 51
	v_writelane_b32 v253, s15, 52
	s_cselect_b64 s[14:15], -1, 0
	s_add_i32 s19, s84, s3
	v_writelane_b32 v253, s14, 53
	s_cmp_lt_i32 s19, 8
	s_mul_i32 s7, s7, 17
	v_writelane_b32 v253, s15, 54
	s_cselect_b64 s[14:15], -1, 0
	s_lshr_b32 s13, s93, 29
	v_writelane_b32 v253, s14, 55
	s_add_i32 s13, s92, s13
	s_mul_i32 s12, s12, 5
	v_writelane_b32 v253, s15, 56
	s_ashr_i32 s14, s13, 3
	s_and_b32 s13, s13, -8
	s_sub_i32 s13, s92, s13
	s_lshl_b32 s15, s13, 5
	s_cmpk_lt_i32 s19, 0xc0
	s_cselect_b64 s[16:17], -1, 0
	v_writelane_b32 v253, s16, 57
	s_nop 1
	v_writelane_b32 v253, s17, 58
	s_lshr_b32 s16, s93, 24
	s_add_i32 s16, s92, s16
	s_and_b32 s16, s16, 0xff00
	s_sub_i32 s16, s92, s16
	s_sext_i32_i16 s17, s16
	s_bfe_u32 s17, s17, 0x3001c
	s_add_i32 s17, s16, s17
	s_and_b32 s18, s17, 0xfff8
	s_sub_i32 s16, s16, s18
	s_sext_i32_i16 s16, s16
	s_sext_i32_i16 s17, s17
	s_ashr_i32 s17, s17, 3
	s_lshl_b32 s18, s16, 5
	s_cmp_lt_i32 s19, 64
	v_writelane_b32 v253, s19, 59
	s_cselect_b64 s[20:21], -1, 0
	v_writelane_b32 v253, s20, 60
	s_cmp_lt_i32 s92, 32
	s_movk_i32 s19, 0xdd
	v_writelane_b32 v253, s21, 61
	s_cselect_b64 s[20:21], -1, 0
	s_cmp_lt_i32 s5, 0
	s_cselect_b32 s19, s19, 0xdc
	s_mul_i32 s5, s19, s5
	s_add_i32 s5, s5, s4
	s_mul_hi_i32 s4, s5, 0x94f2095
	s_lshr_b32 s19, s4, 31
	s_ashr_i32 s4, s4, 4
	s_add_i32 s4, s4, s19
	s_mul_i32 s19, s4, 0x1b8
	s_sub_i32 s5, s5, s19
	s_bfe_u32 s19, s5, 0x3001c
	v_writelane_b32 v253, s20, 62
	s_add_i32 s19, s5, s19
	s_lshl_b32 s4, s4, 3
	v_writelane_b32 v253, s21, 63
	s_and_b32 s20, s19, 0xfff8
	s_sub_i32 s5, s5, s20
	s_sext_i32_i16 s19, s19
	s_sext_i32_i16 s5, s5
	s_add_i32 s20, s4, s5
	s_ashr_i32 s4, s19, 3
	v_writelane_b32 v254, s4, 0
	s_lshr_b32 s4, s19, 3
	s_cmp_lt_i32 s2, 0
	s_cselect_b32 s2, s7, s8
	s_add_i32 s2, s2, s6
	s_ashr_i32 s5, s2, 31
	s_lshr_b32 s5, s5, 27
	s_add_i32 s5, s2, s5
	s_and_b32 s6, s5, 0xffe0
	s_sub_i32 s2, s2, s6
	s_bfe_i32 s6, s2, 0x80000
	s_bfe_u32 s6, s6, 0x3000c
	s_add_i32 s6, s2, s6
	s_and_b32 s7, s6, 0xf8
	s_sub_i32 s2, s2, s7
	s_ashr_i32 s5, s5, 5
	s_bfe_i32 s6, s6, 0x80000
	s_lshl_b32 s5, s5, 3
	s_sext_i32_i16 s6, s6
	s_sext_i32_i8 s2, s2
	s_add_i32 s22, s5, s2
	s_ashr_i32 s2, s6, 3
	v_writelane_b32 v254, s2, 1
	s_lshr_b32 s2, s6, 3
	s_bfe_i64 s[6:7], s[2:3], 0x100000
	s_lshl_b64 s[6:7], s[6:7], 19
	v_writelane_b32 v254, s6, 2
	s_ashr_i32 s23, s22, 31
	s_mov_b32 s2, s22
	v_writelane_b32 v254, s7, 3
	s_sext_i32_i16 s8, s10
	v_writelane_b32 v254, s2, 4
	s_lshl_b64 s[6:7], s[22:23], 19
	s_cmp_lt_i32 s8, 0
	v_writelane_b32 v254, s3, 5
	v_writelane_b32 v254, s6, 6
	s_cselect_b32 s2, s12, s9
	s_nop 0
	v_writelane_b32 v254, s7, 7
	s_add_i32 s6, s2, s11
	s_ashr_i32 s7, s6, 31
	s_mov_b32 s2, s6
	s_lshl_b64 s[6:7], s[6:7], 19
	v_writelane_b32 v254, s2, 8
	s_cmp_lt_i32 s13, 0
	s_mul_i32 s13, s13, 33
	v_writelane_b32 v254, s3, 9
	s_cselect_b32 s2, s13, s15
	s_add_i32 s2, s2, s14
	s_ashr_i32 s5, s2, 31
	s_lshr_b32 s5, s5, 26
	v_writelane_b32 v254, s6, 10
	s_add_i32 s5, s2, s5
; __device__ __forceinline__ void skinny_proj(Frame& F, int l) {
;     constexpr int NTASK = NPROJ / 128;
;     const bf16_t* W = (const bf16_t*)(F.ws + WS_WIN + l * al1m(SZ_WIN));
;     const int ntile = (MPT / 256) * (NPROJ / 256), nlight = (ntile % F.G) ? F.G - (ntile % F.G) : F.G, first = F.G - nlight;
;     if (F.bid >= first) {
;         bool staged = false;
;         const int nit = first ? 2 : (NTASK + nlight - 1) / nlight;
;         for (int it = 0; it < nit; ++it) { const int task = (F.bid - first) + it * nlight;
;             if (task >= NTASK) break;
;             if (!staged) { skinny_stage<DM>(F.lds, (const bf16_t*)(F.ws + WS_H) + (size_t)MPT * DM, DM, F.tid); staged = true; }
;             const int n0 = task * 128 + F.wave * 16; f32x4 d[2];
;             skinny_tile<DM>(F.lds, W, DM, n0, 0, DM, F.lane, d[0], d[1]);
;             skinny_proj_epi(F, l, n0, d); }
;     } else {
;         for (int qt = first - 1 - F.bid; qt < (NTASK - 2 * nlight) * 4; qt += first) {
;             __syncthreads();
;             skinny_stage<DM>(F.lds, (const bf16_t*)(F.ws + WS_H) + (size_t)MPT * DM, DM, F.tid);
;             const int tile = F.wave & 1, kq = F.wave >> 1, n0 = 2 * nlight * 128 + qt * 32 + tile * 16; f32x4 d[2];
; __device__ __forceinline__ void skinny_glu(Frame& F, int l) {
;     ...
;     for (int task = F.G - 17 - F.bid; task < 8; task += F.G) {
;         if (task < 0) continue;
;         if (!staged) { skinny_stage<1024>(F.lds, Z + (size_t)MPT * 1024, 1024, F.tid); staged = true; }
;         const int n0 = task * 128 + F.wave * 16; f32x4 d[2];
	s_movk_i32 s11, 0x1000
	v_writelane_b32 v254, s7, 11
	s_and_b32 s6, s5, 0xffc0
	s_sub_i32 s2, s2, s6
	s_bfe_i32 s6, s2, 0x80000
	s_bfe_u32 s6, s6, 0x3000c
	s_add_i32 s6, s2, s6
	s_and_b32 s7, s6, 0xf8
	s_sub_i32 s2, s2, s7
	s_ashr_i32 s5, s5, 6
	s_bfe_i32 s6, s6, 0x80000
	s_lshl_b32 s5, s5, 3
	s_sext_i32_i16 s6, s6
	s_sext_i32_i8 s2, s2
	s_add_i32 s12, s5, s2
	s_ashr_i32 s2, s6, 3
	v_writelane_b32 v254, s2, 12
	s_lshr_b32 s2, s6, 3
	s_cmp_lt_i32 s16, 0
	s_mul_i32 s16, s16, 33
	s_cselect_b32 s5, s16, s18
	s_add_i32 s5, s5, s17
	s_ashr_i32 s6, s5, 31
	s_lshr_b32 s6, s6, 26
	s_add_i32 s6, s5, s6
	s_and_b32 s7, s6, 0xffc0
	s_sub_i32 s5, s5, s7
	s_bfe_i32 s7, s5, 0x80000
	s_bfe_u32 s7, s7, 0x3000c
	s_add_i32 s7, s5, s7
	s_and_b32 s8, s7, 0xf8
	s_sub_i32 s5, s5, s8
	s_abs_i32 s8, s84
	s_ashr_i32 s6, s6, 6
	s_bfe_i32 s7, s7, 0x80000
	v_cvt_f32_u32_e32 v1, s8
	s_lshl_b32 s6, s6, 3
	s_sext_i32_i16 s7, s7
	s_sext_i32_i8 s5, s5
	s_add_i32 s14, s6, s5
	s_lshr_b32 s6, s7, 3
	s_ashr_i32 s5, s7, 3
	s_bfe_i64 s[6:7], s[6:7], 0x100000
	v_writelane_b32 v254, s5, 13
	s_lshl_b64 s[6:7], s[6:7], 20
	v_rcp_iflag_f32_e32 v1, v1
	v_writelane_b32 v254, s6, 14
	s_bfe_i64 s[4:5], s[4:5], 0x100000
	s_lshl_b64 s[4:5], s[4:5], 20
	v_writelane_b32 v254, s7, 15
	v_writelane_b32 v254, s4, 16
	v_mul_f32_e32 v1, 0x4f7ffffe, v1
	v_cvt_u32_f32_e32 v1, v1
	v_writelane_b32 v254, s5, 17
	s_bfe_i64 s[4:5], s[2:3], 0x100000
	s_lshl_b64 s[4:5], s[4:5], 19
	v_writelane_b32 v254, s4, 18
	s_mov_b32 s6, s14
	s_ashr_i32 s15, s14, 31
	v_writelane_b32 v254, s5, 19
	v_writelane_b32 v254, s6, 20
	s_sub_i32 s9, 0, s8
	v_readfirstlane_b32 s10, v1
	v_writelane_b32 v254, s7, 21
	s_lshl_b64 s[6:7], s[14:15], 20
	v_writelane_b32 v254, s6, 22
	s_mul_i32 s9, s9, s10
	s_mul_hi_u32 s9, s10, s9
	v_writelane_b32 v254, s7, 23
	s_mov_b32 s6, s20
	s_ashr_i32 s21, s20, 31
	v_writelane_b32 v254, s6, 24
	s_add_i32 s10, s10, s9
	s_mul_hi_u32 s2, s10, 0x6e0
	v_writelane_b32 v254, s7, 25
	s_lshl_b64 s[6:7], s[20:21], 20
	v_writelane_b32 v254, s6, 26
	s_mul_i32 s2, s2, s8
	s_ashr_i32 s13, s12, 31
	v_writelane_b32 v254, s7, 27
	s_mov_b32 s6, s12
	s_sub_i32 s2, 0x6e0, s2
	v_writelane_b32 v254, s6, 28
	s_sub_i32 s4, s2, s8
	s_nop 0
	v_writelane_b32 v254, s7, 29
	s_lshl_b64 s[6:7], s[12:13], 19
	s_cmp_ge_u32 s2, s8
	s_cselect_b32 s2, s4, s2
	s_sub_i32 s4, s2, s8
	s_cmp_ge_u32 s2, s8
	s_cselect_b32 s9, s4, s2
	s_sub_i32 s10, s84, s9
	v_writelane_b32 v254, s6, 30
	s_cmp_ge_i32 s92, s9
	s_cselect_b64 s[4:5], -1, 0
	v_writelane_b32 v254, s7, 31
	v_writelane_b32 v254, s4, 32
	s_cmp_eq_u32 s9, 0
	s_mov_b32 s12, 0xf149f2ca
	v_writelane_b32 v254, s5, 33
	s_cselect_b64 s[4:5], -1, 0
	s_abs_i32 s2, s10
	v_cvt_f32_u32_e32 v1, s2
	v_writelane_b32 v254, s4, 34
	s_mov_b32 s13, 0x80000001
	v_rcp_iflag_f32_e32 v1, v1
	v_writelane_b32 v254, s5, 35
	s_sub_i32 s4, 0, s2
	v_mul_f32_e32 v1, 0x4f7ffffe, v1
	v_cvt_u32_f32_e32 v1, v1
	s_nop 0
	v_readfirstlane_b32 s5, v1
	s_mul_i32 s4, s4, s5
	s_mul_hi_u32 s4, s5, s4
	s_add_i32 s5, s5, s4
	s_add_i32 s4, s10, 0x6d
	s_abs_i32 s6, s4
	s_mul_hi_u32 s5, s6, s5
	s_mul_i32 s7, s5, s2
	s_sub_i32 s6, s6, s7
	s_xor_b32 s4, s4, s10
	s_ashr_i32 s4, s4, 31
	s_add_i32 s7, s5, 1
	s_sub_i32 s8, s6, s2
	s_cmp_ge_u32 s6, s2
	s_cselect_b32 s5, s7, s5
	s_cselect_b32 s6, s8, s6
	s_add_i32 s7, s5, 1
	s_cmp_ge_u32 s6, s2
	s_cselect_b32 s2, s7, s5
	s_xor_b32 s2, s2, s4
	s_sub_i32 s2, s2, s4
	v_writelane_b32 v254, s2, 36
	s_lshl_b32 s2, s10, 3
	s_sub_i32 s4, s92, s9
	s_add_i32 s3, s9, s3
	s_sub_i32 s2, 0x1b8, s2
	v_writelane_b32 v254, s4, 37
	v_writelane_b32 v254, s3, 38
	s_cmp_lt_i32 s3, s2
	v_writelane_b32 v254, s2, 39
	s_cselect_b64 s[2:3], -1, 0
	v_writelane_b32 v254, s2, 40
	s_ashr_i32 s89, s88, 31
	s_lshl_b32 s39, s84, 12
	v_writelane_b32 v254, s3, 41
	s_lshl_b32 s2, s92, 7
	s_lshl_b32 s3, s9, 7
	v_writelane_b32 v254, s9, 42
	s_sub_i32 s4, s2, s3
	v_writelane_b32 v254, s4, 43
	s_lshl_b32 s4, s84, 7
	s_sub_i32 s3, s4, s3
	v_writelane_b32 v254, s3, 44
	s_sub_i32 s2, s4, s2
	v_writelane_b32 v254, s4, 45
	s_addk_i32 s2, 0xfb80
	v_writelane_b32 v254, s2, 46
	v_writelane_b32 v254, s10, 47
	s_lshl_b32 s2, s10, 8
	v_writelane_b32 v254, s2, 48
	s_add_i32 s2, s81, 0xffffe000
	v_writelane_b32 v254, s2, 49
	s_lshl_b32 s2, s92, 4
	v_writelane_b32 v254, s2, 50
	s_lshl_b32 s2, s84, 4
	v_writelane_b32 v252, s2, 8
	s_lshl_b64 s[2:3], s[92:93], 13
	s_add_u32 s2, s2, 0x4000000
	v_writelane_b32 v254, s2, 51
	s_addc_u32 s2, s3, 0
	v_writelane_b32 v254, s2, 52
	s_mul_hi_i32 s3, s88, 0x6e00
	s_mul_i32 s2, s88, 0x6e00
	v_writelane_b32 v252, s2, 10
	s_add_i32 s4, 0, 0x10204
	s_lshl_b64 s[6:7], s[84:85], 13
	v_writelane_b32 v252, s3, 11
	s_add_i32 s2, 0, 0x23020
	v_writelane_b32 v254, s2, 53
	s_add_i32 s2, 0, 0x23024
	v_writelane_b32 v254, s2, 54
	v_writelane_b32 v252, s4, 12
	s_add_i32 s4, 0, 0x49e0
	v_writelane_b32 v254, s4, 55
	s_add_i32 s4, 0, 0x5a20
	v_writelane_b32 v254, s4, 56
	v_writelane_b32 v254, s6, 57
	v_mbcnt_lo_u32_b32 v1, -1, 0
	s_mov_b32 s5, 0
	v_writelane_b32 v254, s7, 58
	s_lshl_b64 s[6:7], s[88:89], 12
	v_writelane_b32 v254, s6, 59
	v_mbcnt_hi_u32_b32 v236, -1, v1
	s_movk_i32 s10, 0xdff
	v_writelane_b32 v254, s7, 60
	s_lshl_b64 s[6:7], s[88:89], 13
	v_writelane_b32 v254, s6, 61
	s_mov_b32 s9, 0x88888889
	s_mov_b32 s3, 0x20600000
	v_writelane_b32 v254, s7, 62
	s_mov_b64 s[6:7], -1
	v_writelane_b32 v254, s6, 63
	s_mov_b32 s2, 0x20000
	s_mov_b32 s4, s5
	v_writelane_b32 v255, s7, 0
	v_writelane_b32 v255, s92, 1
	s_mov_b64 s[6:7], 0x1080
	s_nop 0
	v_writelane_b32 v255, s93, 2
	v_writelane_b32 v255, s82, 3
	s_nop 1
	v_writelane_b32 v255, s83, 4
	v_writelane_b32 v255, s81, 5
	s_branch .LBB0_144

; __device__ __forceinline__ u32x2 pack4(const f32x4& v) { u32x2 w; w.x = pk2(v[0], v[1]); w.y = pk2(v[2], v[3]); return w; }
; __device__ __forceinline__ f32x4 unpack4(const u32x2& x) { return (f32x4){bf2f(x.x & 0xffffu), __uint_as_float(x.x & 0xffff0000u), bf2f(x.y & 0xffffu), __uint_as_float(x.y & 0xffff0000u)}; }
; __device__ __forceinline__ void skinny_pool(Frame& F, int l) {
;     ...
;     for (int task = F.G - 1 - F.bid; task < 8; task += F.G) {
;         if (!staged) { skinny_stage<1024>(F.lds, (const bf16_t*)(F.ws + WS_DIFF) + (size_t)MPT * 1024, 1024, F.tid); staged = true; }
;         const int z = task >> 1, n0 = (task & 1) * 128 + F.wave * 16; f32x4 d[2];
;         skinny_tile<1024>(F.lds, W + (size_t)z * 65536, 256, n0, z * 256, 256, F.lane, d[0], d[1]);
;         const int col = z * 256 + n0 + 4 * (F.lane >> 4);
;         const f32x4 ps = *(const f32x4*)(pscale + col);
; #pragma unroll
;         for (int tt = 0; tt < 2; ++tt) { const int row = MPT + 16 * tt + (F.lane & 15);
;             const f32x4 zf = unpack4(*(const u32x2*)(P + (size_t)row * NPROJ + C_PZ + col));
;             *(u32x2*)(apool + (size_t)row * 1024 + col) = pack4(d[tt] * ps * zf); }
.LBB0_1152:
	v_readlane_b32 s18, v253, 59
	s_nop 3
	s_sub_i32 s18, s18, 24
	s_cmp_lt_u32 s18, 8
	s_cselect_b64 s[18:19], -1, 0
	s_andn2_b64 vcc, exec, s[18:19]
	s_barrier
	s_cbranch_vccnz .LBB0_1165
	s_load_dwordx2 s[18:19], s[0:1], 0x58
	s_lshl_b64 s[20:21], s[4:5], 2
	v_add_u32_e32 v2, 0x1ff, v31
	v_lshrrev_b32_e32 v3, 9, v2
	v_add_u32_e32 v3, 1, v3
	s_waitcnt lgkmcnt(0)
	s_add_u32 s20, s18, s20
	s_addc_u32 s21, s19, s21
	s_mov_b64 s[22:23], 0xc800800
	s_add_u32 s18, s72, 0x1be00000
	v_and_b32_e32 v3, 7, v3
	v_and_b32_e32 v4, 0xe00, v2
	s_movk_i32 s4, 0xe00
	v_lshl_add_u64 v[6:7], v[14:15], 0, s[22:23]
	v_lshlrev_b32_e32 v8, 11, v32
	v_mov_b32_e32 v9, v99
	v_lshl_add_u64 v[12:13], v[12:13], 0, s[22:23]
	v_lshlrev_b32_e32 v14, 11, v30
	v_mov_b32_e32 v15, v99
	s_addc_u32 s19, s73, 0
	v_cmp_ne_u32_e64 s[44:45], s4, v4
	v_cmp_lt_u32_e64 s[46:47], s10, v2
	v_sub_u32_e32 v16, 0, v3
	s_mov_b64 s[22:23], 0
	v_readlane_b32 s4, v253, 59
	s_nop 3
	s_sub_i32 s4, s4, 24
	s_branch .LBB0_1156
